# m2 plus K-loop top ds_read hoist (G1 x2, P7) plus barrier leader inv after XGEN atomic
# speedup vs baseline: 1.0017x; 1.0017x over previous
; __device__ __forceinline__ unsigned xb_add(unsigned* p, unsigned v) { return __hip_atomic_fetch_add(p, v, __ATOMIC_RELAXED, __HIP_MEMORY_SCOPE_AGENT); }
; __device__ __forceinline__ void xcd_barrier(const XcdBarrier& b) {
;     ...
;             __builtin_amdgcn_fence(__ATOMIC_ACQUIRE, "agent");
;             xb_add(&bar[XB_XGEN(b.x)], 1u);
;             asm volatile("s_waitcnt vmcnt(0)" ::: "memory");
.LBB0_353:
	s_or_b64 exec, exec, s[6:7]
	s_mov_b64 s[6:7], exec
	v_mbcnt_lo_u32_b32 v0, s6, 0
	v_mbcnt_hi_u32_b32 v0, s7, v0
	v_cmp_eq_u32_e32 vcc, 0, v0
	s_waitcnt vmcnt(0)
	s_and_saveexec_b64 s[14:15], vcc
	s_cbranch_execz .LBB0_355
	s_bcnt1_i32_b64 s2, s[6:7]
	v_mov_b32_e32 v0, 0x2000
	v_mov_b32_e32 v1, s2
	global_atomic_add v0, v1, s[4:5] offset:1024
.LBB0_355:
	s_or_b64 exec, exec, s[14:15]
	buffer_inv sc1
	s_waitcnt vmcnt(0)

.LBB0_369:
	ds_read_b128 v[80:83], v180
	ds_read_b128 v[84:87], v180 offset:1024
	ds_read_b128 v[88:91], v180 offset:2048
	ds_read_b128 v[92:95], v180 offset:3072
	ds_read_b128 v[144:147], v181
	ds_read_b128 v[148:151], v181 offset:1024
	ds_read_b128 v[152:155], v181 offset:2048
	ds_read_b128 v[156:159], v181 offset:3072
	ds_read_b128 v[160:163], v182
	ds_read_b128 v[164:167], v182 offset:1024
	ds_read_b128 v[172:175], v182 offset:2048
	ds_read_b128 v[186:189], v182 offset:3072
	ds_read_b128 v[190:193], v182 offset:4096
	ds_read_b128 v[194:197], v182 offset:5120
	ds_read_b128 v[198:201], v182 offset:6144
	ds_read_b128 v[202:205], v182 offset:7168
	s_add_i32 s65, s67, 2
	s_cmp_lt_u32 s67, 14
	s_cselect_b32 s2, 0, -16
	s_cselect_b32 s70, s66, s47
	s_cselect_b32 s72, s64, s8
	s_add_i32 s74, s65, s2
	s_ashr_i32 s71, s70, 31
	s_ashr_i32 s73, s72, 31
	s_ashr_i32 s75, s74, 31
	s_lshl_b64 s[70:71], s[70:71], 19
	s_lshl_b64 s[72:73], s[72:73], 19
	s_lshl_b64 s[74:75], s[74:75], 7
	s_add_u32 s2, s23, s72
	s_addc_u32 s6, s26, s73
	s_cmp_lt_u32 s67, 13
	s_cselect_b32 s7, 0, -16
	s_cselect_b32 s72, s66, s47
	s_cselect_b32 s76, s64, s8
	s_add_i32 s7, s7, s67
	s_add_i32 s78, s7, 3
	s_ashr_i32 s73, s72, 31
	s_ashr_i32 s77, s76, 31
	s_ashr_i32 s79, s78, 31
	s_lshl_b64 s[72:73], s[72:73], 19
	s_lshl_b64 s[76:77], s[76:77], 19
	s_lshl_b64 s[78:79], s[78:79], 7
	s_add_u32 s76, s23, s76
	s_addc_u32 s77, s26, s77
	s_add_u32 s7, s21, s70
	s_addc_u32 s44, s22, s71
	s_add_u32 s86, s7, s74
	s_addc_u32 s87, s44, s75
	s_add_u32 s7, s21, s72
	s_addc_u32 s44, s22, s73
	s_add_u32 s70, s7, s78
	s_addc_u32 s71, s44, s79
	s_add_u32 s92, s2, s74
	s_addc_u32 s93, s6, s75
	s_add_u32 s44, s68, 0x40000
	s_addc_u32 s45, s69, 0
	s_add_u32 s6, s68, 0x60000
	s_addc_u32 s7, s69, 0
	s_add_u32 s96, s92, 0x20000
	s_addc_u32 s97, s93, 0
	s_add_u32 s94, s92, 0x40000
	s_addc_u32 s95, s93, 0
	s_add_u32 s90, s92, 0x60000
	s_addc_u32 s91, s93, 0
	s_add_u32 s88, s86, 0x20000
	s_addc_u32 s89, s87, 0
	s_add_u32 s84, s86, 0x40000
	s_addc_u32 s85, s87, 0
	s_add_u32 s82, s86, 0x60000
	s_addc_u32 s83, s87, 0
	s_add_u32 s80, s76, s78
	s_addc_u32 s81, s77, s79
	s_add_u32 s78, s80, 0x20000
	s_addc_u32 s79, s81, 0
	s_add_u32 s76, s80, 0x40000
	s_addc_u32 s77, s81, 0
	s_add_u32 s74, s80, 0x60000
	s_addc_u32 s75, s81, 0
	s_add_u32 s72, s70, 0x20000
	s_addc_u32 s73, s71, 0
	s_add_u32 s68, s68, 0x100
	s_addc_u32 s69, s69, 0
	s_cmp_gt_u32 s67, 13
	s_mov_b32 s2, m0
	s_mov_b32 m0, s20
	s_nop 0
	global_load_lds_dwordx4 v178, s[44:45]
	s_mov_b32 m0, s2
	s_nop 0
	s_mov_b32 s2, m0
	s_mov_b32 m0, s19
	s_nop 0
	global_load_lds_dwordx4 v178, s[6:7]
	s_mov_b32 m0, s2
	s_waitcnt vmcnt(8)
	s_waitcnt lgkmcnt(0)
	s_barrier
	s_setprio 1
	s_waitcnt lgkmcnt(7)
	v_mfma_f32_16x16x32_bf16 v[132:135], v[80:83], v[160:163], v[132:135]
	v_mfma_f32_16x16x32_bf16 v[128:131], v[88:91], v[160:163], v[128:131]
	s_waitcnt lgkmcnt(5)
	v_mfma_f32_16x16x32_bf16 v[116:119], v[80:83], v[172:175], v[116:119]
	v_mfma_f32_16x16x32_bf16 v[112:115], v[88:91], v[172:175], v[112:115]
	s_waitcnt lgkmcnt(3)
	v_mfma_f32_16x16x32_bf16 v[100:103], v[80:83], v[190:193], v[100:103]
	v_mfma_f32_16x16x32_bf16 v[96:99], v[88:91], v[190:193], v[96:99]
	s_waitcnt lgkmcnt(1)
	v_mfma_f32_16x16x32_bf16 v[68:71], v[80:83], v[198:201], v[68:71]
	v_mfma_f32_16x16x32_bf16 v[64:67], v[88:91], v[198:201], v[64:67]
	v_mfma_f32_16x16x32_bf16 v[132:135], v[84:87], v[164:167], v[132:135]
	v_mfma_f32_16x16x32_bf16 v[128:131], v[92:95], v[164:167], v[128:131]
	v_mfma_f32_16x16x32_bf16 v[116:119], v[84:87], v[186:189], v[116:119]
	v_mfma_f32_16x16x32_bf16 v[112:115], v[92:95], v[186:189], v[112:115]
	v_mfma_f32_16x16x32_bf16 v[100:103], v[84:87], v[194:197], v[100:103]
	v_mfma_f32_16x16x32_bf16 v[96:99], v[92:95], v[194:197], v[96:99]
	s_waitcnt lgkmcnt(0)
	v_mfma_f32_16x16x32_bf16 v[68:71], v[84:87], v[202:205], v[68:71]
	v_mfma_f32_16x16x32_bf16 v[64:67], v[92:95], v[202:205], v[64:67]
	s_setprio 0
	s_setprio 1
	v_mfma_f32_16x16x32_bf16 v[140:143], v[144:147], v[160:163], v[140:143]
	v_mfma_f32_16x16x32_bf16 v[136:139], v[152:155], v[160:163], v[136:139]
	v_mfma_f32_16x16x32_bf16 v[124:127], v[144:147], v[172:175], v[124:127]
	v_mfma_f32_16x16x32_bf16 v[120:123], v[152:155], v[172:175], v[120:123]
	v_mfma_f32_16x16x32_bf16 v[108:111], v[144:147], v[190:193], v[108:111]
	v_mfma_f32_16x16x32_bf16 v[104:107], v[152:155], v[190:193], v[104:107]
	v_mfma_f32_16x16x32_bf16 v[76:79], v[144:147], v[198:201], v[76:79]
	v_mfma_f32_16x16x32_bf16 v[72:75], v[152:155], v[198:201], v[72:75]
	v_mfma_f32_16x16x32_bf16 v[140:143], v[148:151], v[164:167], v[140:143]
	v_mfma_f32_16x16x32_bf16 v[136:139], v[156:159], v[164:167], v[136:139]
	v_mfma_f32_16x16x32_bf16 v[124:127], v[148:151], v[186:189], v[124:127]
	v_mfma_f32_16x16x32_bf16 v[120:123], v[156:159], v[186:189], v[120:123]
	v_mfma_f32_16x16x32_bf16 v[108:111], v[148:151], v[194:197], v[108:111]
	v_mfma_f32_16x16x32_bf16 v[104:107], v[156:159], v[194:197], v[104:107]
	v_mfma_f32_16x16x32_bf16 v[76:79], v[148:151], v[202:205], v[76:79]
	v_mfma_f32_16x16x32_bf16 v[72:75], v[156:159], v[202:205], v[72:75]
	s_setprio 0
	s_barrier
	ds_read_b128 v[160:163], v182 offset:16384
	ds_read_b128 v[164:167], v182 offset:17408
	ds_read_b128 v[172:175], v182 offset:18432
	ds_read_b128 v[186:189], v182 offset:19456
	ds_read_b128 v[190:193], v182 offset:20480
	ds_read_b128 v[194:197], v182 offset:21504
	ds_read_b128 v[198:201], v182 offset:22528
	ds_read_b128 v[202:205], v182 offset:23552
	s_mov_b32 s2, m0
	s_mov_b32 m0, s33
	s_nop 0
	global_load_lds_dwordx4 v179, s[92:93]
	s_mov_b32 m0, s2
	s_nop 0
	s_mov_b32 s2, m0
	s_mov_b32 m0, s35
	s_nop 0
	global_load_lds_dwordx4 v179, s[96:97]
	s_mov_b32 m0, s2
	s_nop 0
	s_mov_b32 s2, m0
	s_mov_b32 m0, s38
	s_nop 0
	global_load_lds_dwordx4 v179, s[94:95]
	s_mov_b32 m0, s2
	s_nop 0
	s_mov_b32 s2, m0
	s_mov_b32 m0, s39
	s_nop 0
	global_load_lds_dwordx4 v179, s[90:91]
	s_mov_b32 m0, s2
	s_nop 0
	s_mov_b32 s2, m0
	s_mov_b32 m0, s27
	s_nop 0
	global_load_lds_dwordx4 v178, s[86:87]
	s_mov_b32 m0, s2
	s_nop 0
	s_mov_b32 s2, m0
	s_mov_b32 m0, s40
	s_nop 0
	global_load_lds_dwordx4 v178, s[88:89]
	s_mov_b32 m0, s2
	s_waitcnt vmcnt(8)
	s_waitcnt lgkmcnt(0)
	s_barrier
	s_setprio 1
	s_waitcnt lgkmcnt(7)
	v_mfma_f32_16x16x32_bf16 v[52:55], v[80:83], v[160:163], v[52:55]
	v_mfma_f32_16x16x32_bf16 v[48:51], v[88:91], v[160:163], v[48:51]
	s_waitcnt lgkmcnt(5)
	v_mfma_f32_16x16x32_bf16 v[36:39], v[80:83], v[172:175], v[36:39]
	v_mfma_f32_16x16x32_bf16 v[32:35], v[88:91], v[172:175], v[32:35]
	s_waitcnt lgkmcnt(3)
	v_mfma_f32_16x16x32_bf16 v[20:23], v[80:83], v[190:193], v[20:23]
	v_mfma_f32_16x16x32_bf16 v[16:19], v[88:91], v[190:193], v[16:19]
	s_waitcnt lgkmcnt(1)
	v_mfma_f32_16x16x32_bf16 v[4:7], v[80:83], v[198:201], v[4:7]
	v_mfma_f32_16x16x32_bf16 v[0:3], v[88:91], v[198:201], v[0:3]
	v_mfma_f32_16x16x32_bf16 v[52:55], v[84:87], v[164:167], v[52:55]
	v_mfma_f32_16x16x32_bf16 v[48:51], v[92:95], v[164:167], v[48:51]
	v_mfma_f32_16x16x32_bf16 v[36:39], v[84:87], v[186:189], v[36:39]
	v_mfma_f32_16x16x32_bf16 v[32:35], v[92:95], v[186:189], v[32:35]
	v_mfma_f32_16x16x32_bf16 v[20:23], v[84:87], v[194:197], v[20:23]
	v_mfma_f32_16x16x32_bf16 v[16:19], v[92:95], v[194:197], v[16:19]
	s_waitcnt lgkmcnt(0)
	v_mfma_f32_16x16x32_bf16 v[4:7], v[84:87], v[202:205], v[4:7]
	v_mfma_f32_16x16x32_bf16 v[0:3], v[92:95], v[202:205], v[0:3]
	s_setprio 0
	s_setprio 1
	v_mfma_f32_16x16x32_bf16 v[60:63], v[144:147], v[160:163], v[60:63]
	v_mfma_f32_16x16x32_bf16 v[56:59], v[152:155], v[160:163], v[56:59]
	v_mfma_f32_16x16x32_bf16 v[44:47], v[144:147], v[172:175], v[44:47]
	v_mfma_f32_16x16x32_bf16 v[40:43], v[152:155], v[172:175], v[40:43]
	v_mfma_f32_16x16x32_bf16 v[28:31], v[144:147], v[190:193], v[28:31]
	v_mfma_f32_16x16x32_bf16 v[24:27], v[152:155], v[190:193], v[24:27]
	v_mfma_f32_16x16x32_bf16 v[12:15], v[144:147], v[198:201], v[12:15]
	v_mfma_f32_16x16x32_bf16 v[8:11], v[152:155], v[198:201], v[8:11]
	v_mfma_f32_16x16x32_bf16 v[60:63], v[148:151], v[164:167], v[60:63]
	v_mfma_f32_16x16x32_bf16 v[56:59], v[156:159], v[164:167], v[56:59]
	v_mfma_f32_16x16x32_bf16 v[44:47], v[148:151], v[186:189], v[44:47]
	v_mfma_f32_16x16x32_bf16 v[40:43], v[156:159], v[186:189], v[40:43]
	v_mfma_f32_16x16x32_bf16 v[28:31], v[148:151], v[194:197], v[28:31]
	v_mfma_f32_16x16x32_bf16 v[24:27], v[156:159], v[194:197], v[24:27]
	v_mfma_f32_16x16x32_bf16 v[12:15], v[148:151], v[202:205], v[12:15]
	v_mfma_f32_16x16x32_bf16 v[8:11], v[156:159], v[202:205], v[8:11]
	s_setprio 0
	s_barrier
	ds_read_b128 v[80:83], v183
	ds_read_b128 v[84:87], v183 offset:1024
	ds_read_b128 v[88:91], v183 offset:2048
	ds_read_b128 v[92:95], v183 offset:3072
	ds_read_b128 v[144:147], v184
	ds_read_b128 v[148:151], v184 offset:1024
	ds_read_b128 v[152:155], v184 offset:2048
	ds_read_b128 v[156:159], v184 offset:3072
	ds_read_b128 v[160:163], v182 offset:32768
	ds_read_b128 v[164:167], v182 offset:33792
	ds_read_b128 v[172:175], v182 offset:34816
	ds_read_b128 v[186:189], v182 offset:35840
	ds_read_b128 v[190:193], v182 offset:36864
	ds_read_b128 v[194:197], v182 offset:37888
	ds_read_b128 v[198:201], v182 offset:38912
	ds_read_b128 v[202:205], v182 offset:39936
	s_mov_b32 s2, m0
	s_mov_b32 m0, s41
	s_nop 0
	global_load_lds_dwordx4 v178, s[84:85]
	s_mov_b32 m0, s2
	s_nop 0
	s_mov_b32 s2, m0
	s_mov_b32 m0, s48
	s_nop 0
	global_load_lds_dwordx4 v178, s[82:83]
	s_mov_b32 m0, s2
	s_waitcnt vmcnt(8)
	s_waitcnt lgkmcnt(0)
	s_barrier
; __device__ __forceinline__ int lane_id() { int l; asm volatile("v_mbcnt_lo_u32_b32 %0, -1, 0\n\tv_mbcnt_hi_u32_b32 %0, -1, %0" : "=v"(l)); return l; }
; #define PG8_BAR __builtin_amdgcn_s_barrier()
; template <class Epi, class Sched, bool ALIGN_EPI = false, bool SP2 = true>
; __device__ __forceinline__ void gemm_phase(PG8_LAS unsigned char* lds, const Gemm g, const Sched& S, const Epi& E, int wid) {
;     ...
;         if constexpr (TWO) { const int l1_ = lane_id(); aoff = lds_byte(wr * 64 + (l1_ & 15), (l1_ >> 4) * 8); boff = lds_byte(wc * 32 + (l1_ & 15), (l1_ >> 4) * 8); }
;         if constexpr (ZC) { { const int t = 0; PG8_TRIP(F8A || F8S1, true); }
;             for (int t = 2; t < nt1; t += 2) PG8_TRIP(F8A || F8S1, false); }
;         else { for (int t = 0; t < nt1; t += 2) PG8_TRIP(F8A || F8S1, false); }
;         if constexpr (TWO) { E.mid(acc, cur, wr, wc, fr, fq);
;             { const int l2_ = lane_id(); aoff = lds_byte(wr * 64 + (l2_ & 15), (l2_ >> 4) * 8); boff = lds_byte(wc * 32 + (l2_ & 15), (l2_ >> 4) * 8); }
;             for (int t = nt1; t < nt; t += 2) PG8_TRIP(F8A, false); }
;         if constexpr (ALIGN_EPI) { if (wr == 0) PG8_BAR; }
	s_setprio 1
	s_waitcnt lgkmcnt(7)
	v_mfma_f32_16x16x32_bf16 v[132:135], v[80:83], v[160:163], v[132:135]
	v_mfma_f32_16x16x32_bf16 v[128:131], v[88:91], v[160:163], v[128:131]
	s_waitcnt lgkmcnt(5)
	v_mfma_f32_16x16x32_bf16 v[116:119], v[80:83], v[172:175], v[116:119]
	v_mfma_f32_16x16x32_bf16 v[112:115], v[88:91], v[172:175], v[112:115]
	s_waitcnt lgkmcnt(3)
	v_mfma_f32_16x16x32_bf16 v[100:103], v[80:83], v[190:193], v[100:103]
	v_mfma_f32_16x16x32_bf16 v[96:99], v[88:91], v[190:193], v[96:99]
	s_waitcnt lgkmcnt(1)
	v_mfma_f32_16x16x32_bf16 v[68:71], v[80:83], v[198:201], v[68:71]
	v_mfma_f32_16x16x32_bf16 v[64:67], v[88:91], v[198:201], v[64:67]
	v_mfma_f32_16x16x32_bf16 v[132:135], v[84:87], v[164:167], v[132:135]
	v_mfma_f32_16x16x32_bf16 v[128:131], v[92:95], v[164:167], v[128:131]
	v_mfma_f32_16x16x32_bf16 v[116:119], v[84:87], v[186:189], v[116:119]
	v_mfma_f32_16x16x32_bf16 v[112:115], v[92:95], v[186:189], v[112:115]
	v_mfma_f32_16x16x32_bf16 v[100:103], v[84:87], v[194:197], v[100:103]
	v_mfma_f32_16x16x32_bf16 v[96:99], v[92:95], v[194:197], v[96:99]
	s_waitcnt lgkmcnt(0)
	v_mfma_f32_16x16x32_bf16 v[68:71], v[84:87], v[202:205], v[68:71]
	v_mfma_f32_16x16x32_bf16 v[64:67], v[92:95], v[202:205], v[64:67]
	s_setprio 0
	s_setprio 1
	v_mfma_f32_16x16x32_bf16 v[140:143], v[144:147], v[160:163], v[140:143]
	v_mfma_f32_16x16x32_bf16 v[136:139], v[152:155], v[160:163], v[136:139]
	v_mfma_f32_16x16x32_bf16 v[124:127], v[144:147], v[172:175], v[124:127]
	v_mfma_f32_16x16x32_bf16 v[120:123], v[152:155], v[172:175], v[120:123]
	v_mfma_f32_16x16x32_bf16 v[108:111], v[144:147], v[190:193], v[108:111]
	v_mfma_f32_16x16x32_bf16 v[104:107], v[152:155], v[190:193], v[104:107]
	v_mfma_f32_16x16x32_bf16 v[76:79], v[144:147], v[198:201], v[76:79]
	v_mfma_f32_16x16x32_bf16 v[72:75], v[152:155], v[198:201], v[72:75]
	v_mfma_f32_16x16x32_bf16 v[140:143], v[148:151], v[164:167], v[140:143]
	v_mfma_f32_16x16x32_bf16 v[136:139], v[156:159], v[164:167], v[136:139]
	v_mfma_f32_16x16x32_bf16 v[124:127], v[148:151], v[186:189], v[124:127]
	v_mfma_f32_16x16x32_bf16 v[120:123], v[156:159], v[186:189], v[120:123]
	v_mfma_f32_16x16x32_bf16 v[108:111], v[148:151], v[194:197], v[108:111]
	v_mfma_f32_16x16x32_bf16 v[104:107], v[156:159], v[194:197], v[104:107]
	v_mfma_f32_16x16x32_bf16 v[76:79], v[148:151], v[202:205], v[76:79]
	v_mfma_f32_16x16x32_bf16 v[72:75], v[156:159], v[202:205], v[72:75]
	s_setprio 0
	s_barrier
	ds_read_b128 v[160:163], v182 offset:49152
	ds_read_b128 v[164:167], v182 offset:50176
	ds_read_b128 v[172:175], v182 offset:51200
	ds_read_b128 v[186:189], v182 offset:52224
	ds_read_b128 v[190:193], v182 offset:53248
	ds_read_b128 v[194:197], v182 offset:54272
	ds_read_b128 v[198:201], v182 offset:55296
	ds_read_b128 v[202:205], v182 offset:56320
	s_mov_b32 s2, m0
	s_mov_b32 m0, s49
	s_nop 0
	global_load_lds_dwordx4 v179, s[80:81]
	s_mov_b32 m0, s2
	s_nop 0
	s_mov_b32 s2, m0
	s_mov_b32 m0, s50
	s_nop 0
	global_load_lds_dwordx4 v179, s[78:79]
	s_mov_b32 m0, s2
	s_nop 0
	s_mov_b32 s2, m0
	s_mov_b32 m0, s53
	s_nop 0
	global_load_lds_dwordx4 v179, s[76:77]
	s_mov_b32 m0, s2
	s_nop 0
	s_mov_b32 s2, m0
	s_mov_b32 m0, s54
	s_nop 0
	global_load_lds_dwordx4 v179, s[74:75]
	s_mov_b32 m0, s2
	s_nop 0
	s_mov_b32 s2, m0
	s_mov_b32 m0, s51
	s_nop 0
	global_load_lds_dwordx4 v178, s[70:71]
	s_mov_b32 m0, s2
	s_nop 0
	s_mov_b32 s2, m0
	s_mov_b32 m0, s52
	s_nop 0
	global_load_lds_dwordx4 v178, s[72:73]
	s_mov_b32 m0, s2
	s_waitcnt vmcnt(8)
	s_waitcnt lgkmcnt(0)
	s_barrier
	s_setprio 1
	s_waitcnt lgkmcnt(7)
	v_mfma_f32_16x16x32_bf16 v[52:55], v[80:83], v[160:163], v[52:55]
	v_mfma_f32_16x16x32_bf16 v[48:51], v[88:91], v[160:163], v[48:51]
	s_waitcnt lgkmcnt(5)
	v_mfma_f32_16x16x32_bf16 v[36:39], v[80:83], v[172:175], v[36:39]
	v_mfma_f32_16x16x32_bf16 v[32:35], v[88:91], v[172:175], v[32:35]
	s_waitcnt lgkmcnt(3)
	v_mfma_f32_16x16x32_bf16 v[20:23], v[80:83], v[190:193], v[20:23]
	v_mfma_f32_16x16x32_bf16 v[16:19], v[88:91], v[190:193], v[16:19]
	s_waitcnt lgkmcnt(1)
	v_mfma_f32_16x16x32_bf16 v[4:7], v[80:83], v[198:201], v[4:7]
	v_mfma_f32_16x16x32_bf16 v[0:3], v[88:91], v[198:201], v[0:3]
	v_mfma_f32_16x16x32_bf16 v[52:55], v[84:87], v[164:167], v[52:55]
	v_mfma_f32_16x16x32_bf16 v[48:51], v[92:95], v[164:167], v[48:51]
	v_mfma_f32_16x16x32_bf16 v[36:39], v[84:87], v[186:189], v[36:39]
	v_mfma_f32_16x16x32_bf16 v[32:35], v[92:95], v[186:189], v[32:35]
	v_mfma_f32_16x16x32_bf16 v[20:23], v[84:87], v[194:197], v[20:23]
	v_mfma_f32_16x16x32_bf16 v[16:19], v[92:95], v[194:197], v[16:19]
	s_waitcnt lgkmcnt(0)
	v_mfma_f32_16x16x32_bf16 v[4:7], v[84:87], v[202:205], v[4:7]
	v_mfma_f32_16x16x32_bf16 v[0:3], v[92:95], v[202:205], v[0:3]
	s_setprio 0
	s_setprio 1
	v_mfma_f32_16x16x32_bf16 v[60:63], v[144:147], v[160:163], v[60:63]
	v_mfma_f32_16x16x32_bf16 v[56:59], v[152:155], v[160:163], v[56:59]
	v_mfma_f32_16x16x32_bf16 v[44:47], v[144:147], v[172:175], v[44:47]
	v_mfma_f32_16x16x32_bf16 v[40:43], v[152:155], v[172:175], v[40:43]
	v_mfma_f32_16x16x32_bf16 v[28:31], v[144:147], v[190:193], v[28:31]
	v_mfma_f32_16x16x32_bf16 v[24:27], v[152:155], v[190:193], v[24:27]
	v_mfma_f32_16x16x32_bf16 v[12:15], v[144:147], v[198:201], v[12:15]
	v_mfma_f32_16x16x32_bf16 v[8:11], v[152:155], v[198:201], v[8:11]
	v_mfma_f32_16x16x32_bf16 v[60:63], v[148:151], v[164:167], v[60:63]
	v_mfma_f32_16x16x32_bf16 v[56:59], v[156:159], v[164:167], v[56:59]
	v_mfma_f32_16x16x32_bf16 v[44:47], v[148:151], v[186:189], v[44:47]
	v_mfma_f32_16x16x32_bf16 v[40:43], v[156:159], v[186:189], v[40:43]
	v_mfma_f32_16x16x32_bf16 v[28:31], v[148:151], v[194:197], v[28:31]
	v_mfma_f32_16x16x32_bf16 v[24:27], v[156:159], v[194:197], v[24:27]
	v_mfma_f32_16x16x32_bf16 v[12:15], v[148:151], v[202:205], v[12:15]
	v_mfma_f32_16x16x32_bf16 v[8:11], v[156:159], v[202:205], v[8:11]
	s_setprio 0
	s_barrier
	s_mov_b32 s67, s65
	s_cbranch_scc0 .LBB0_369
	s_and_b64 vcc, exec, s[16:17]
	s_cbranch_vccz .LBB0_372
	s_barrier

.LBB0_411:
	ds_read_b128 v[112:115], v182
	ds_read_b128 v[116:119], v182 offset:1024
	ds_read_b128 v[120:123], v182 offset:2048
	ds_read_b128 v[124:127], v182 offset:3072
	ds_read_b128 v[144:147], v183
	ds_read_b128 v[148:151], v183 offset:1024
	ds_read_b128 v[152:155], v183 offset:2048
	ds_read_b128 v[156:159], v183 offset:3072
	ds_read_b128 v[160:163], v184
	ds_read_b128 v[164:167], v184 offset:1024
	ds_read_b128 v[188:191], v184 offset:2048
	ds_read_b128 v[192:195], v184 offset:3072
	ds_read_b128 v[196:199], v184 offset:4096
	ds_read_b128 v[200:203], v184 offset:5120
	ds_read_b128 v[204:207], v184 offset:6144
	ds_read_b128 v[208:211], v184 offset:7168
	s_add_i32 s22, s21, 2
	s_cmp_lt_u32 s21, 6
	s_cselect_b32 s2, 0, -8
	s_cselect_b32 s6, s64, s9
	s_cselect_b32 s26, s66, s8
	s_add_i32 s68, s22, s2
	s_ashr_i32 s7, s6, 31
	s_ashr_i32 s27, s26, 31
	s_ashr_i32 s69, s68, 31
	s_lshl_b64 s[6:7], s[6:7], 18
	s_lshl_b64 s[26:27], s[26:27], 18
	s_lshl_b64 s[70:71], s[68:69], 7
	s_add_u32 s2, s96, s26
	s_addc_u32 s23, s97, s27
	s_cmp_lt_u32 s21, 5
	s_cselect_b32 s27, 0, -8
	s_cselect_b32 s26, s64, s9
	s_cselect_b32 s68, s66, s8
	s_add_i32 s65, s27, s21
	s_add_i32 s72, s65, 3
	s_ashr_i32 s27, s26, 31
	s_ashr_i32 s69, s68, 31
	s_ashr_i32 s73, s72, 31
	s_lshl_b64 s[26:27], s[26:27], 18
	s_lshl_b64 s[68:69], s[68:69], 18
	s_lshl_b64 s[72:73], s[72:73], 7
	s_add_u32 s65, s96, s68
	s_addc_u32 s67, s97, s69
	s_add_u32 s6, s57, s6
	s_addc_u32 s7, s63, s7
	s_add_u32 s84, s6, s70
	s_addc_u32 s85, s7, s71
	s_add_u32 s6, s57, s26
	s_addc_u32 s7, s63, s27
	s_add_u32 s68, s6, s72
	s_addc_u32 s69, s7, s73
	s_add_u32 s88, s2, s70
	s_addc_u32 s89, s23, s71
	s_add_u32 s6, s19, 0x20000
	s_addc_u32 s7, s20, 0
	s_add_u32 s26, s19, 0x30000
	s_addc_u32 s27, s20, 0
	s_add_u32 s94, s88, 0x10000
	s_addc_u32 s95, s89, 0
	s_add_u32 s92, s88, 0x20000
	s_addc_u32 s93, s89, 0
	s_add_u32 s90, s88, 0x30000
	s_addc_u32 s91, s89, 0
	s_add_u32 s86, s84, 0x10000
	s_addc_u32 s87, s85, 0
	s_add_u32 s82, s84, 0x20000
	s_addc_u32 s83, s85, 0
	s_add_u32 s80, s84, 0x30000
	s_addc_u32 s81, s85, 0
	s_add_u32 s78, s65, s72
	s_addc_u32 s79, s67, s73
	s_add_u32 s76, s78, 0x10000
	s_addc_u32 s77, s79, 0
	s_add_u32 s74, s78, 0x20000
	s_addc_u32 s75, s79, 0
	s_add_u32 s72, s78, 0x30000
	s_addc_u32 s73, s79, 0
	s_add_u32 s70, s68, 0x10000
	s_addc_u32 s71, s69, 0
	s_add_u32 s19, s19, 0x100
	s_addc_u32 s20, s20, 0
	s_cmp_gt_u32 s21, 5
	s_mov_b32 s2, m0
	s_mov_b32 m0, s38
	s_nop 0
	global_load_lds_dwordx4 v180, s[6:7]
	s_mov_b32 m0, s2
	s_nop 0
	s_mov_b32 s2, m0
	s_mov_b32 m0, s49
	s_nop 0
	global_load_lds_dwordx4 v180, s[26:27]
	s_mov_b32 m0, s2
	s_waitcnt vmcnt(8)
	s_waitcnt lgkmcnt(0)
	s_barrier
	s_setprio 1
	s_waitcnt lgkmcnt(6)
	v_mfma_scale_f32_16x16x128_f8f6f4 v[140:143], v[112:119], v[160:167], v[140:143], v185, v185 op_sel_hi:[0,0,0]
	v_mfma_scale_f32_16x16x128_f8f6f4 v[136:139], v[120:127], v[160:167], v[136:139], v185, v185 op_sel_hi:[0,0,0]
	s_waitcnt lgkmcnt(4)
	v_mfma_scale_f32_16x16x128_f8f6f4 v[108:111], v[112:119], v[188:195], v[108:111], v185, v185 op_sel_hi:[0,0,0]
	v_mfma_scale_f32_16x16x128_f8f6f4 v[104:107], v[120:127], v[188:195], v[104:107], v185, v185 op_sel_hi:[0,0,0]
	s_waitcnt lgkmcnt(2)
	v_mfma_scale_f32_16x16x128_f8f6f4 v[174:177], v[112:119], v[196:203], v[92:95], v185, v185 op_sel_hi:[0,0,0]
	v_mfma_scale_f32_16x16x128_f8f6f4 v[212:215], v[120:127], v[196:203], v[88:91], v185, v185 op_sel_hi:[0,0,0]
	s_waitcnt lgkmcnt(0)
	v_mfma_scale_f32_16x16x128_f8f6f4 v[216:219], v[112:119], v[204:211], v[76:79], v185, v185 op_sel_hi:[0,0,0]
	v_mfma_scale_f32_16x16x128_f8f6f4 v[220:223], v[120:127], v[204:211], v[72:75], v185, v185 op_sel_hi:[0,0,0]
	s_setprio 0
	s_setprio 1
	v_mfma_scale_f32_16x16x128_f8f6f4 v[132:135], v[144:151], v[160:167], v[132:135], v185, v185 op_sel_hi:[0,0,0]
	v_mfma_scale_f32_16x16x128_f8f6f4 v[128:131], v[152:159], v[160:167], v[128:131], v185, v185 op_sel_hi:[0,0,0]
	v_mfma_scale_f32_16x16x128_f8f6f4 v[100:103], v[144:151], v[188:195], v[100:103], v185, v185 op_sel_hi:[0,0,0]
	v_mfma_scale_f32_16x16x128_f8f6f4 v[96:99], v[152:159], v[188:195], v[96:99], v185, v185 op_sel_hi:[0,0,0]
	v_mfma_scale_f32_16x16x128_f8f6f4 v[160:163], v[144:151], v[196:203], v[84:87], v185, v185 op_sel_hi:[0,0,0]
	v_mfma_scale_f32_16x16x128_f8f6f4 v[164:167], v[152:159], v[196:203], v[80:83], v185, v185 op_sel_hi:[0,0,0]
	v_mfma_scale_f32_16x16x128_f8f6f4 v[188:191], v[144:151], v[204:211], v[68:71], v185, v185 op_sel_hi:[0,0,0]
	v_mfma_scale_f32_16x16x128_f8f6f4 v[192:195], v[152:159], v[204:211], v[64:67], v185, v185 op_sel_hi:[0,0,0]
	s_setprio 0
	s_barrier
	s_nop 4
	ds_read_b128 v[64:67], v184 offset:16384
	ds_read_b128 v[68:71], v184 offset:17408
	ds_read_b128 v[72:75], v184 offset:18432
	ds_read_b128 v[76:79], v184 offset:19456
	ds_read_b128 v[80:83], v184 offset:20480
	ds_read_b128 v[84:87], v184 offset:21504
	ds_read_b128 v[88:91], v184 offset:22528
	ds_read_b128 v[92:95], v184 offset:23552
	s_mov_b32 s2, m0
	s_mov_b32 m0, s24
	s_nop 0
	global_load_lds_dwordx4 v181, s[88:89]
	s_mov_b32 m0, s2
	s_nop 0
	s_mov_b32 s2, m0
	s_mov_b32 m0, s25
	s_nop 0
	global_load_lds_dwordx4 v181, s[94:95]
	s_mov_b32 m0, s2
	s_nop 0
	s_mov_b32 s2, m0
	s_mov_b32 m0, s16
	s_nop 0
	global_load_lds_dwordx4 v181, s[92:93]
	s_mov_b32 m0, s2
	s_nop 0
	s_mov_b32 s2, m0
	s_mov_b32 m0, s17
	s_nop 0
	global_load_lds_dwordx4 v181, s[90:91]
	s_mov_b32 m0, s2
	s_nop 0
	s_mov_b32 s2, m0
	s_mov_b32 m0, s55
	s_nop 0
	global_load_lds_dwordx4 v180, s[84:85]
	s_mov_b32 m0, s2
	s_nop 0
	s_mov_b32 s2, m0
	s_mov_b32 m0, s36
	s_nop 0
	global_load_lds_dwordx4 v180, s[86:87]
	s_mov_b32 m0, s2
	s_waitcnt vmcnt(8)
	s_waitcnt lgkmcnt(0)
	s_barrier
	s_setprio 1
	s_waitcnt lgkmcnt(6)
	v_mfma_scale_f32_16x16x128_f8f6f4 v[60:63], v[112:119], v[64:71], v[60:63], v185, v185 op_sel_hi:[0,0,0]
	v_mfma_scale_f32_16x16x128_f8f6f4 v[56:59], v[120:127], v[64:71], v[56:59], v185, v185 op_sel_hi:[0,0,0]
	s_waitcnt lgkmcnt(4)
	v_mfma_scale_f32_16x16x128_f8f6f4 v[196:199], v[112:119], v[72:79], v[44:47], v185, v185 op_sel_hi:[0,0,0]
	v_mfma_scale_f32_16x16x128_f8f6f4 v[200:203], v[120:127], v[72:79], v[40:43], v185, v185 op_sel_hi:[0,0,0]
	s_waitcnt lgkmcnt(2)
	v_mfma_scale_f32_16x16x128_f8f6f4 v[204:207], v[112:119], v[80:87], v[28:31], v185, v185 op_sel_hi:[0,0,0]
	v_mfma_scale_f32_16x16x128_f8f6f4 v[208:211], v[120:127], v[80:87], v[24:27], v185, v185 op_sel_hi:[0,0,0]
	s_waitcnt lgkmcnt(0)
	v_mfma_scale_f32_16x16x128_f8f6f4 v[224:227], v[112:119], v[88:95], v[12:15], v185, v185 op_sel_hi:[0,0,0]
	v_mfma_scale_f32_16x16x128_f8f6f4 v[228:231], v[120:127], v[88:95], v[8:11], v185, v185 op_sel_hi:[0,0,0]
	s_setprio 0
	s_setprio 1
	v_mfma_scale_f32_16x16x128_f8f6f4 v[52:55], v[144:151], v[64:71], v[52:55], v185, v185 op_sel_hi:[0,0,0]
	v_mfma_scale_f32_16x16x128_f8f6f4 v[48:51], v[152:159], v[64:71], v[48:51], v185, v185 op_sel_hi:[0,0,0]
	v_mfma_scale_f32_16x16x128_f8f6f4 v[232:235], v[144:151], v[72:79], v[36:39], v185, v185 op_sel_hi:[0,0,0]
	v_mfma_scale_f32_16x16x128_f8f6f4 v[236:239], v[152:159], v[72:79], v[32:35], v185, v185 op_sel_hi:[0,0,0]
	v_mfma_scale_f32_16x16x128_f8f6f4 v[240:243], v[144:151], v[80:87], v[20:23], v185, v185 op_sel_hi:[0,0,0]
	v_mfma_scale_f32_16x16x128_f8f6f4 v[244:247], v[152:159], v[80:87], v[16:19], v185, v185 op_sel_hi:[0,0,0]
	v_mfma_scale_f32_16x16x128_f8f6f4 v[248:251], v[144:151], v[88:95], v[4:7], v185, v185 op_sel_hi:[0,0,0]
	v_mfma_scale_f32_16x16x128_f8f6f4 v[168:171], v[152:159], v[88:95], v[0:3], v185, v185 op_sel_hi:[0,0,0]
	s_setprio 0
	s_barrier
	s_nop 4
	ds_read_b128 v[0:3], v186
	ds_read_b128 v[4:7], v186 offset:1024
	ds_read_b128 v[16:19], v186 offset:2048
	ds_read_b128 v[20:23], v186 offset:3072
	ds_read_b128 v[112:115], v187
	ds_read_b128 v[116:119], v187 offset:1024
	ds_read_b128 v[120:123], v187 offset:2048
	ds_read_b128 v[124:127], v187 offset:3072
	ds_read_b128 v[8:11], v184 offset:32768
	ds_read_b128 v[12:15], v184 offset:33792
	ds_read_b128 v[24:27], v184 offset:34816
	ds_read_b128 v[28:31], v184 offset:35840
	ds_read_b128 v[32:35], v184 offset:36864
	ds_read_b128 v[36:39], v184 offset:37888
	ds_read_b128 v[40:43], v184 offset:38912
	ds_read_b128 v[44:47], v184 offset:39936
	s_mov_b32 s2, m0
	s_mov_b32 m0, s37
	s_nop 0
	global_load_lds_dwordx4 v180, s[82:83]
	s_mov_b32 m0, s2
	s_nop 0
	s_mov_b32 s2, m0
	s_mov_b32 m0, s54
	s_nop 0
	global_load_lds_dwordx4 v180, s[80:81]
	s_mov_b32 m0, s2
	s_waitcnt vmcnt(8)
	s_waitcnt lgkmcnt(0)
	s_barrier
	s_setprio 1
	s_waitcnt lgkmcnt(6)
	v_mfma_scale_f32_16x16x128_f8f6f4 v[140:143], v[0:7], v[8:15], v[140:143], v185, v185 op_sel_hi:[0,0,0]
	v_mfma_scale_f32_16x16x128_f8f6f4 v[136:139], v[16:23], v[8:15], v[136:139], v185, v185 op_sel_hi:[0,0,0]
	s_waitcnt lgkmcnt(4)
	v_mfma_scale_f32_16x16x128_f8f6f4 v[108:111], v[0:7], v[24:31], v[108:111], v185, v185 op_sel_hi:[0,0,0]
	v_mfma_scale_f32_16x16x128_f8f6f4 v[104:107], v[16:23], v[24:31], v[104:107], v185, v185 op_sel_hi:[0,0,0]
	s_waitcnt lgkmcnt(2)
	v_mfma_scale_f32_16x16x128_f8f6f4 v[92:95], v[0:7], v[32:39], v[174:177], v185, v185 op_sel_hi:[0,0,0]
	v_mfma_scale_f32_16x16x128_f8f6f4 v[88:91], v[16:23], v[32:39], v[212:215], v185, v185 op_sel_hi:[0,0,0]
	s_waitcnt lgkmcnt(0)
	v_mfma_scale_f32_16x16x128_f8f6f4 v[76:79], v[0:7], v[40:47], v[216:219], v185, v185 op_sel_hi:[0,0,0]
	v_mfma_scale_f32_16x16x128_f8f6f4 v[72:75], v[16:23], v[40:47], v[220:223], v185, v185 op_sel_hi:[0,0,0]
	s_setprio 0
	s_setprio 1
	v_mfma_scale_f32_16x16x128_f8f6f4 v[132:135], v[112:119], v[8:15], v[132:135], v185, v185 op_sel_hi:[0,0,0]
	v_mfma_scale_f32_16x16x128_f8f6f4 v[128:131], v[120:127], v[8:15], v[128:131], v185, v185 op_sel_hi:[0,0,0]
	v_mfma_scale_f32_16x16x128_f8f6f4 v[100:103], v[112:119], v[24:31], v[100:103], v185, v185 op_sel_hi:[0,0,0]
	v_mfma_scale_f32_16x16x128_f8f6f4 v[96:99], v[120:127], v[24:31], v[96:99], v185, v185 op_sel_hi:[0,0,0]
	v_mfma_scale_f32_16x16x128_f8f6f4 v[84:87], v[112:119], v[32:39], v[160:163], v185, v185 op_sel_hi:[0,0,0]
	v_mfma_scale_f32_16x16x128_f8f6f4 v[80:83], v[120:127], v[32:39], v[164:167], v185, v185 op_sel_hi:[0,0,0]
	v_mfma_scale_f32_16x16x128_f8f6f4 v[68:71], v[112:119], v[40:47], v[188:191], v185, v185 op_sel_hi:[0,0,0]
	v_mfma_scale_f32_16x16x128_f8f6f4 v[64:67], v[120:127], v[40:47], v[192:195], v185, v185 op_sel_hi:[0,0,0]
	s_setprio 0
	s_barrier
; __device__ __forceinline__ int lane_id() { int l; asm volatile("v_mbcnt_lo_u32_b32 %0, -1, 0\n\tv_mbcnt_hi_u32_b32 %0, -1, %0" : "=v"(l)); return l; }
; #define PG8_BAR __builtin_amdgcn_s_barrier()
; template <class Epi, class Sched, bool ALIGN_EPI = false, bool SP2 = true>
; __device__ __forceinline__ void gemm_phase(PG8_LAS unsigned char* lds, const Gemm g, const Sched& S, const Epi& E, int wid) {
;     ...
;         if constexpr (TWO) { const int l1_ = lane_id(); aoff = lds_byte(wr * 64 + (l1_ & 15), (l1_ >> 4) * 8); boff = lds_byte(wc * 32 + (l1_ & 15), (l1_ >> 4) * 8); }
;         if constexpr (ZC) { { const int t = 0; PG8_TRIP(F8A || F8S1, true); }
;             for (int t = 2; t < nt1; t += 2) PG8_TRIP(F8A || F8S1, false); }
;         else { for (int t = 0; t < nt1; t += 2) PG8_TRIP(F8A || F8S1, false); }
;         if constexpr (TWO) { E.mid(acc, cur, wr, wc, fr, fq);
;             { const int l2_ = lane_id(); aoff = lds_byte(wr * 64 + (l2_ & 15), (l2_ >> 4) * 8); boff = lds_byte(wc * 32 + (l2_ & 15), (l2_ >> 4) * 8); }
;             for (int t = nt1; t < nt; t += 2) PG8_TRIP(F8A, false); }
;         if constexpr (ALIGN_EPI) { if (wr == 0) PG8_BAR; }
	ds_read_b128 v[32:35], v184 offset:49152
	ds_read_b128 v[36:39], v184 offset:50176
	ds_read_b128 v[144:147], v184 offset:51200
	ds_read_b128 v[148:151], v184 offset:52224
	ds_read_b128 v[152:155], v184 offset:53248
	ds_read_b128 v[156:159], v184 offset:54272
	ds_read_b128 v[160:163], v184 offset:55296
	ds_read_b128 v[164:167], v184 offset:56320
	s_mov_b32 s2, m0
	s_mov_b32 m0, s33
	s_nop 0
	global_load_lds_dwordx4 v181, s[78:79]
	s_mov_b32 m0, s2
	s_nop 0
	s_mov_b32 s2, m0
	s_mov_b32 m0, s42
	s_nop 0
	global_load_lds_dwordx4 v181, s[76:77]
	s_mov_b32 m0, s2
	s_nop 0
	s_mov_b32 s2, m0
	s_mov_b32 m0, s35
	s_nop 0
	global_load_lds_dwordx4 v181, s[74:75]
	s_mov_b32 m0, s2
	s_nop 0
	s_mov_b32 s2, m0
	s_mov_b32 m0, s52
	s_nop 0
	global_load_lds_dwordx4 v181, s[72:73]
	s_mov_b32 m0, s2
	s_nop 0
	s_mov_b32 s2, m0
	s_mov_b32 m0, s43
	s_nop 0
	global_load_lds_dwordx4 v180, s[68:69]
	s_mov_b32 m0, s2
	s_nop 0
	s_mov_b32 s2, m0
	s_mov_b32 m0, s34
	s_nop 0
	global_load_lds_dwordx4 v180, s[70:71]
	s_mov_b32 m0, s2
	s_waitcnt vmcnt(8)
	s_waitcnt lgkmcnt(0)
	s_barrier
	s_setprio 1
	s_waitcnt lgkmcnt(6)
	v_mfma_scale_f32_16x16x128_f8f6f4 v[60:63], v[0:7], v[32:39], v[60:63], v185, v185 op_sel_hi:[0,0,0]
	v_mfma_scale_f32_16x16x128_f8f6f4 v[56:59], v[16:23], v[32:39], v[56:59], v185, v185 op_sel_hi:[0,0,0]
	s_waitcnt lgkmcnt(4)
	v_mfma_scale_f32_16x16x128_f8f6f4 v[44:47], v[0:7], v[144:151], v[196:199], v185, v185 op_sel_hi:[0,0,0]
	v_mfma_scale_f32_16x16x128_f8f6f4 v[40:43], v[16:23], v[144:151], v[200:203], v185, v185 op_sel_hi:[0,0,0]
	s_waitcnt lgkmcnt(2)
	v_mfma_scale_f32_16x16x128_f8f6f4 v[28:31], v[0:7], v[152:159], v[204:207], v185, v185 op_sel_hi:[0,0,0]
	v_mfma_scale_f32_16x16x128_f8f6f4 v[24:27], v[16:23], v[152:159], v[208:211], v185, v185 op_sel_hi:[0,0,0]
	s_waitcnt lgkmcnt(0)
	v_mfma_scale_f32_16x16x128_f8f6f4 v[12:15], v[0:7], v[160:167], v[224:227], v185, v185 op_sel_hi:[0,0,0]
	v_mfma_scale_f32_16x16x128_f8f6f4 v[8:11], v[16:23], v[160:167], v[228:231], v185, v185 op_sel_hi:[0,0,0]
	s_setprio 0
	s_setprio 1
	v_mfma_scale_f32_16x16x128_f8f6f4 v[52:55], v[112:119], v[32:39], v[52:55], v185, v185 op_sel_hi:[0,0,0]
	v_mfma_scale_f32_16x16x128_f8f6f4 v[48:51], v[120:127], v[32:39], v[48:51], v185, v185 op_sel_hi:[0,0,0]
	v_mfma_scale_f32_16x16x128_f8f6f4 v[36:39], v[112:119], v[144:151], v[232:235], v185, v185 op_sel_hi:[0,0,0]
	v_mfma_scale_f32_16x16x128_f8f6f4 v[32:35], v[120:127], v[144:151], v[236:239], v185, v185 op_sel_hi:[0,0,0]
	v_mfma_scale_f32_16x16x128_f8f6f4 v[20:23], v[112:119], v[152:159], v[240:243], v185, v185 op_sel_hi:[0,0,0]
	v_mfma_scale_f32_16x16x128_f8f6f4 v[16:19], v[120:127], v[152:159], v[244:247], v185, v185 op_sel_hi:[0,0,0]
	v_mfma_scale_f32_16x16x128_f8f6f4 v[4:7], v[112:119], v[160:167], v[248:251], v185, v185 op_sel_hi:[0,0,0]
	v_mfma_scale_f32_16x16x128_f8f6f4 v[0:3], v[120:127], v[160:167], v[168:171], v185, v185 op_sel_hi:[0,0,0]
	s_setprio 0
	s_barrier
	s_mov_b32 s21, s22
	s_cbranch_scc0 .LBB0_411
	s_and_b64 vcc, exec, s[14:15]
	s_cbranch_vccz .LBB0_414
	s_barrier

; __device__ __forceinline__ int lane_id() { int l; asm volatile("v_mbcnt_lo_u32_b32 %0, -1, 0\n\tv_mbcnt_hi_u32_b32 %0, -1, %0" : "=v"(l)); return l; }
; __device__ __forceinline__ unsigned xb_ld(unsigned* p)              { return __hip_atomic_load(p, __ATOMIC_RELAXED, __HIP_MEMORY_SCOPE_AGENT); }
; __device__ __forceinline__ unsigned xb_add(unsigned* p, unsigned v) { return __hip_atomic_fetch_add(p, v, __ATOMIC_RELAXED, __HIP_MEMORY_SCOPE_AGENT); }
; #define XB_SPIN(cond, bar) do { unsigned _sp = 0; while (cond) { __builtin_amdgcn_s_sleep(1); \
;     if ((++_sp & 255u) == 0u) { if (xb_ld(&(bar)[XB_TMO])) break; if (_sp > XB_SPIN_CAP) { atomicAdd(&(bar)[XB_TMO], 1u); break; } } } } while (0)
; __device__ __forceinline__ void xcd_wait(const XcdBarrier& b, const XcdTok& t) {
;     if (b.wave == 0 && lane_id() == 0) {
;         unsigned* bar = b.bar;
;         if (t.role >= 1) {
;             if (t.role == 1) XB_SPIN(xb_ld(&bar[XB_TOPGEN]) == t.tg, bar);
;             __builtin_amdgcn_fence(__ATOMIC_ACQUIRE, "agent");
;             xb_add(&bar[XB_XGEN(b.x)], 1u);
;             asm volatile("s_waitcnt vmcnt(0)" ::: "memory");
.LBB0_608:
	s_or_b64 exec, exec, s[18:19]
	s_mov_b64 s[4:5], exec
	v_mbcnt_lo_u32_b32 v67, s4, 0
	v_mbcnt_hi_u32_b32 v67, s5, v67
	v_cmp_eq_u32_e32 vcc, 0, v67
	s_waitcnt vmcnt(0) lgkmcnt(0)
	s_and_saveexec_b64 s[18:19], vcc
	s_cbranch_execz .LBB0_610
	v_readlane_b32 s1, v254, 8
	s_lshl_b32 s1, s1, 8
	v_readlane_b32 s12, v254, 6
	v_readlane_b32 s13, v254, 7
	s_add_u32 s12, s12, s1
	s_addc_u32 s13, s13, 0
	s_bcnt1_i32_b64 s1, s[4:5]
	v_mov_b32_e32 v67, 0x2000
	v_mov_b32_e32 v68, s1
	global_atomic_add v67, v68, s[12:13] offset:1024
.LBB0_610:
	s_or_b64 exec, exec, s[18:19]
	buffer_inv sc1
	s_waitcnt vmcnt(0)

.LBB0_932:
	ds_read_b128 v[128:131], v180
	ds_read_b128 v[132:135], v180 offset:1024
	ds_read_b128 v[136:139], v180 offset:2048
	ds_read_b128 v[140:143], v180 offset:3072
	ds_read_b128 v[144:147], v181
	ds_read_b128 v[148:151], v181 offset:1024
	ds_read_b128 v[152:155], v181 offset:2048
	ds_read_b128 v[156:159], v181 offset:3072
	ds_read_b128 v[160:163], v182
	ds_read_b128 v[170:173], v182 offset:1024
	ds_read_b128 v[174:177], v182 offset:2048
	ds_read_b128 v[188:191], v182 offset:3072
	ds_read_b128 v[192:195], v182 offset:4096
	ds_read_b128 v[196:199], v182 offset:5120
	ds_read_b128 v[200:203], v182 offset:6144
	ds_read_b128 v[204:207], v182 offset:7168
	s_add_i32 s23, s96, 2
	s_cmp_lt_u32 s96, 14
	s_cselect_b32 s9, 0, -16
	s_cselect_b32 s8, s22, s94
	s_cselect_b32 s24, s4, s95
	s_add_i32 s26, s23, s9
	s_ashr_i32 s9, s8, 31
	s_ashr_i32 s25, s24, 31
	s_ashr_i32 s27, s26, 31
	s_lshl_b64 s[8:9], s[8:9], 19
	s_lshl_b64 s[24:25], s[24:25], 19
	s_lshl_b64 s[26:27], s[26:27], 7
	s_add_u32 s40, s21, s24
	s_addc_u32 s41, s33, s25
	s_cmp_lt_u32 s96, 13
	s_cselect_b32 s25, 0, -16
	s_cselect_b32 s24, s22, s94
	s_cselect_b32 s36, s4, s95
	s_add_i32 s38, s25, s96
	s_add_i32 s38, s38, 3
	s_ashr_i32 s25, s24, 31
	s_ashr_i32 s37, s36, 31
	s_ashr_i32 s39, s38, 31
	s_lshl_b64 s[24:25], s[24:25], 19
	s_lshl_b64 s[36:37], s[36:37], 19
	s_lshl_b64 s[38:39], s[38:39], 7
	s_add_u32 s36, s21, s36
	s_addc_u32 s37, s33, s37
	s_add_u32 s8, s12, s8
	s_addc_u32 s9, s13, s9
	s_add_u32 s46, s8, s26
	s_addc_u32 s47, s9, s27
	s_add_u32 s8, s12, s24
	s_addc_u32 s9, s13, s25
	s_add_u32 s8, s8, s38
	s_addc_u32 s9, s9, s39
	s_add_u32 s56, s40, s26
	s_addc_u32 s57, s41, s27
	s_add_u32 s76, s6, 0x40000
	s_addc_u32 s77, s7, 0
	s_add_u32 s78, s6, 0x60000
	s_addc_u32 s79, s7, 0
	s_add_u32 s60, s56, 0x20000
	s_addc_u32 s61, s57, 0
	s_add_u32 s58, s56, 0x40000
	s_addc_u32 s59, s57, 0
	s_add_u32 s54, s56, 0x60000
	s_addc_u32 s55, s57, 0
	s_add_u32 s52, s46, 0x20000
	s_addc_u32 s53, s47, 0
	s_add_u32 s44, s46, 0x40000
	s_addc_u32 s45, s47, 0
	s_add_u32 s42, s46, 0x60000
	s_addc_u32 s43, s47, 0
	s_add_u32 s40, s36, s38
	s_addc_u32 s41, s37, s39
	s_add_u32 s38, s40, 0x20000
	s_addc_u32 s39, s41, 0
	s_add_u32 s36, s40, 0x40000
	s_addc_u32 s37, s41, 0
	s_add_u32 s26, s40, 0x60000
	s_addc_u32 s27, s41, 0
	s_add_u32 s24, s8, 0x20000
	s_addc_u32 s25, s9, 0
	s_add_u32 s6, s6, 0x100
	s_addc_u32 s7, s7, 0
	s_cmp_gt_u32 s96, 13
	s_mov_b32 s96, m0
	s_mov_b32 m0, s85
	s_nop 0
	global_load_lds_dwordx4 v179, s[76:77]
	s_mov_b32 m0, s96
	s_mov_b32 s76, m0
	s_mov_b32 m0, s87
	s_nop 0
	global_load_lds_dwordx4 v179, s[78:79]
	s_mov_b32 m0, s76
	s_waitcnt vmcnt(8)
	s_waitcnt lgkmcnt(0)
	s_barrier
	s_setprio 1
	s_waitcnt lgkmcnt(7)
	v_mfma_f32_16x16x32_bf16 v[124:127], v[128:131], v[160:163], v[124:127]
	v_mfma_f32_16x16x32_bf16 v[108:111], v[136:139], v[160:163], v[108:111]
	s_waitcnt lgkmcnt(5)
	v_mfma_f32_16x16x32_bf16 v[24:27], v[128:131], v[174:177], v[24:27]
	v_mfma_f32_16x16x32_bf16 v[16:19], v[136:139], v[174:177], v[16:19]
	s_waitcnt lgkmcnt(3)
	v_mfma_f32_16x16x32_bf16 v[0:3], v[128:131], v[192:195], v[0:3]
	v_mfma_f32_16x16x32_bf16 v[4:7], v[136:139], v[192:195], v[4:7]
	s_waitcnt lgkmcnt(1)
	v_mfma_f32_16x16x32_bf16 v[32:35], v[128:131], v[200:203], v[32:35]
	v_mfma_f32_16x16x32_bf16 v[36:39], v[136:139], v[200:203], v[36:39]
	v_mfma_f32_16x16x32_bf16 v[124:127], v[132:135], v[170:173], v[124:127]
	v_mfma_f32_16x16x32_bf16 v[108:111], v[140:143], v[170:173], v[108:111]
	v_mfma_f32_16x16x32_bf16 v[24:27], v[132:135], v[188:191], v[24:27]
	v_mfma_f32_16x16x32_bf16 v[16:19], v[140:143], v[188:191], v[16:19]
	v_mfma_f32_16x16x32_bf16 v[0:3], v[132:135], v[196:199], v[0:3]
	v_mfma_f32_16x16x32_bf16 v[4:7], v[140:143], v[196:199], v[4:7]
	s_waitcnt lgkmcnt(0)
	v_mfma_f32_16x16x32_bf16 v[32:35], v[132:135], v[204:207], v[32:35]
	v_mfma_f32_16x16x32_bf16 v[36:39], v[140:143], v[204:207], v[36:39]
	s_setprio 0
	s_setprio 1
	v_mfma_f32_16x16x32_bf16 v[120:123], v[144:147], v[160:163], v[120:123]
	v_mfma_f32_16x16x32_bf16 v[104:107], v[152:155], v[160:163], v[104:107]
	v_mfma_f32_16x16x32_bf16 v[28:31], v[144:147], v[174:177], v[28:31]
	v_mfma_f32_16x16x32_bf16 v[20:23], v[152:155], v[174:177], v[20:23]
	v_mfma_f32_16x16x32_bf16 v[8:11], v[144:147], v[192:195], v[8:11]
	v_mfma_f32_16x16x32_bf16 v[12:15], v[152:155], v[192:195], v[12:15]
	v_mfma_f32_16x16x32_bf16 v[40:43], v[144:147], v[200:203], v[40:43]
	v_mfma_f32_16x16x32_bf16 v[44:47], v[152:155], v[200:203], v[44:47]
	v_mfma_f32_16x16x32_bf16 v[120:123], v[148:151], v[170:173], v[120:123]
	v_mfma_f32_16x16x32_bf16 v[104:107], v[156:159], v[170:173], v[104:107]
	v_mfma_f32_16x16x32_bf16 v[28:31], v[148:151], v[188:191], v[28:31]
	v_mfma_f32_16x16x32_bf16 v[20:23], v[156:159], v[188:191], v[20:23]
	v_mfma_f32_16x16x32_bf16 v[8:11], v[148:151], v[196:199], v[8:11]
	v_mfma_f32_16x16x32_bf16 v[12:15], v[156:159], v[196:199], v[12:15]
	v_mfma_f32_16x16x32_bf16 v[40:43], v[148:151], v[204:207], v[40:43]
	v_mfma_f32_16x16x32_bf16 v[44:47], v[156:159], v[204:207], v[44:47]
	s_setprio 0
	s_barrier
	ds_read_b128 v[160:163], v182 offset:16384
	ds_read_b128 v[170:173], v182 offset:17408
	ds_read_b128 v[174:177], v182 offset:18432
	ds_read_b128 v[188:191], v182 offset:19456
	ds_read_b128 v[192:195], v182 offset:20480
	ds_read_b128 v[196:199], v182 offset:21504
	ds_read_b128 v[200:203], v182 offset:22528
	ds_read_b128 v[204:207], v182 offset:23552
	s_mov_b32 s76, m0
	s_mov_b32 m0, s35
	s_nop 0
	global_load_lds_dwordx4 v179, s[56:57]
	s_mov_b32 m0, s76
	s_mov_b32 s56, m0
	s_mov_b32 m0, s3
	s_nop 0
	global_load_lds_dwordx4 v179, s[60:61]
	s_mov_b32 m0, s56
	s_nop 0
	s_mov_b32 s56, m0
	s_mov_b32 m0, s68
	s_nop 0
	global_load_lds_dwordx4 v179, s[58:59]
	s_mov_b32 m0, s56
	s_nop 0
	s_mov_b32 s56, m0
	s_mov_b32 m0, s75
	s_nop 0
	global_load_lds_dwordx4 v179, s[54:55]
	s_mov_b32 m0, s56
	s_mov_b32 s54, m0
	s_mov_b32 m0, s34
	s_nop 0
	global_load_lds_dwordx4 v179, s[46:47]
	s_mov_b32 m0, s54
	s_mov_b32 s46, m0
	s_mov_b32 m0, s62
	s_nop 0
	global_load_lds_dwordx4 v179, s[52:53]
	s_mov_b32 m0, s46
	s_waitcnt vmcnt(8)
	s_waitcnt lgkmcnt(0)
	s_barrier
	s_setprio 1
	s_waitcnt lgkmcnt(7)
	v_mfma_f32_16x16x32_bf16 v[56:59], v[128:131], v[160:163], v[56:59]
	v_mfma_f32_16x16x32_bf16 v[48:51], v[136:139], v[160:163], v[48:51]
	s_waitcnt lgkmcnt(5)
	v_mfma_f32_16x16x32_bf16 v[64:67], v[128:131], v[174:177], v[64:67]
	v_mfma_f32_16x16x32_bf16 v[68:71], v[136:139], v[174:177], v[68:71]
	s_waitcnt lgkmcnt(3)
	v_mfma_f32_16x16x32_bf16 v[80:83], v[128:131], v[192:195], v[80:83]
	v_mfma_f32_16x16x32_bf16 v[84:87], v[136:139], v[192:195], v[84:87]
	s_waitcnt lgkmcnt(1)
	v_mfma_f32_16x16x32_bf16 v[100:103], v[128:131], v[200:203], v[100:103]
	v_mfma_f32_16x16x32_bf16 v[96:99], v[136:139], v[200:203], v[96:99]
	v_mfma_f32_16x16x32_bf16 v[56:59], v[132:135], v[170:173], v[56:59]
	v_mfma_f32_16x16x32_bf16 v[48:51], v[140:143], v[170:173], v[48:51]
	v_mfma_f32_16x16x32_bf16 v[64:67], v[132:135], v[188:191], v[64:67]
	v_mfma_f32_16x16x32_bf16 v[68:71], v[140:143], v[188:191], v[68:71]
	v_mfma_f32_16x16x32_bf16 v[80:83], v[132:135], v[196:199], v[80:83]
	v_mfma_f32_16x16x32_bf16 v[84:87], v[140:143], v[196:199], v[84:87]
	s_waitcnt lgkmcnt(0)
	v_mfma_f32_16x16x32_bf16 v[100:103], v[132:135], v[204:207], v[100:103]
	v_mfma_f32_16x16x32_bf16 v[96:99], v[140:143], v[204:207], v[96:99]
	s_setprio 0
	s_setprio 1
	v_mfma_f32_16x16x32_bf16 v[60:63], v[144:147], v[160:163], v[60:63]
	v_mfma_f32_16x16x32_bf16 v[52:55], v[152:155], v[160:163], v[52:55]
	v_mfma_f32_16x16x32_bf16 v[72:75], v[144:147], v[174:177], v[72:75]
	v_mfma_f32_16x16x32_bf16 v[76:79], v[152:155], v[174:177], v[76:79]
	v_mfma_f32_16x16x32_bf16 v[88:91], v[144:147], v[192:195], v[88:91]
	v_mfma_f32_16x16x32_bf16 v[92:95], v[152:155], v[192:195], v[92:95]
	v_mfma_f32_16x16x32_bf16 v[116:119], v[144:147], v[200:203], v[116:119]
	v_mfma_f32_16x16x32_bf16 v[112:115], v[152:155], v[200:203], v[112:115]
	v_mfma_f32_16x16x32_bf16 v[60:63], v[148:151], v[170:173], v[60:63]
	v_mfma_f32_16x16x32_bf16 v[52:55], v[156:159], v[170:173], v[52:55]
	v_mfma_f32_16x16x32_bf16 v[72:75], v[148:151], v[188:191], v[72:75]
	v_mfma_f32_16x16x32_bf16 v[76:79], v[156:159], v[188:191], v[76:79]
	v_mfma_f32_16x16x32_bf16 v[88:91], v[148:151], v[196:199], v[88:91]
	v_mfma_f32_16x16x32_bf16 v[92:95], v[156:159], v[196:199], v[92:95]
	v_mfma_f32_16x16x32_bf16 v[116:119], v[148:151], v[204:207], v[116:119]
	v_mfma_f32_16x16x32_bf16 v[112:115], v[156:159], v[204:207], v[112:115]
	s_setprio 0
	s_barrier
	ds_read_b128 v[128:131], v183
	ds_read_b128 v[132:135], v183 offset:1024
	ds_read_b128 v[136:139], v183 offset:2048
	ds_read_b128 v[140:143], v183 offset:3072
	ds_read_b128 v[144:147], v184
	ds_read_b128 v[148:151], v184 offset:1024
	ds_read_b128 v[152:155], v184 offset:2048
	ds_read_b128 v[156:159], v184 offset:3072
	ds_read_b128 v[160:163], v182 offset:32768
	ds_read_b128 v[170:173], v182 offset:33792
	ds_read_b128 v[174:177], v182 offset:34816
	ds_read_b128 v[188:191], v182 offset:35840
	ds_read_b128 v[192:195], v182 offset:36864
	ds_read_b128 v[196:199], v182 offset:37888
	ds_read_b128 v[200:203], v182 offset:38912
	ds_read_b128 v[204:207], v182 offset:39936
	s_mov_b32 s46, m0
	s_mov_b32 m0, s63
	s_nop 0
	global_load_lds_dwordx4 v179, s[44:45]
	s_mov_b32 m0, s46
	s_mov_b32 s44, m0
	s_mov_b32 m0, s64
	s_nop 0
	global_load_lds_dwordx4 v179, s[42:43]
	s_mov_b32 m0, s44
	s_waitcnt vmcnt(8)
	s_waitcnt lgkmcnt(0)
	s_barrier
	s_setprio 1
	s_waitcnt lgkmcnt(7)
	v_mfma_f32_16x16x32_bf16 v[124:127], v[128:131], v[160:163], v[124:127]
	v_mfma_f32_16x16x32_bf16 v[108:111], v[136:139], v[160:163], v[108:111]
	s_waitcnt lgkmcnt(5)
	v_mfma_f32_16x16x32_bf16 v[24:27], v[128:131], v[174:177], v[24:27]
	v_mfma_f32_16x16x32_bf16 v[16:19], v[136:139], v[174:177], v[16:19]
	s_waitcnt lgkmcnt(3)
	v_mfma_f32_16x16x32_bf16 v[0:3], v[128:131], v[192:195], v[0:3]
	v_mfma_f32_16x16x32_bf16 v[4:7], v[136:139], v[192:195], v[4:7]
	s_waitcnt lgkmcnt(1)
	v_mfma_f32_16x16x32_bf16 v[32:35], v[128:131], v[200:203], v[32:35]
	v_mfma_f32_16x16x32_bf16 v[36:39], v[136:139], v[200:203], v[36:39]
	v_mfma_f32_16x16x32_bf16 v[124:127], v[132:135], v[170:173], v[124:127]
	v_mfma_f32_16x16x32_bf16 v[108:111], v[140:143], v[170:173], v[108:111]
	v_mfma_f32_16x16x32_bf16 v[24:27], v[132:135], v[188:191], v[24:27]
	v_mfma_f32_16x16x32_bf16 v[16:19], v[140:143], v[188:191], v[16:19]
	v_mfma_f32_16x16x32_bf16 v[0:3], v[132:135], v[196:199], v[0:3]
	v_mfma_f32_16x16x32_bf16 v[4:7], v[140:143], v[196:199], v[4:7]
	s_waitcnt lgkmcnt(0)
	v_mfma_f32_16x16x32_bf16 v[32:35], v[132:135], v[204:207], v[32:35]
	v_mfma_f32_16x16x32_bf16 v[36:39], v[140:143], v[204:207], v[36:39]
	s_setprio 0
	s_setprio 1
	v_mfma_f32_16x16x32_bf16 v[120:123], v[144:147], v[160:163], v[120:123]
	v_mfma_f32_16x16x32_bf16 v[104:107], v[152:155], v[160:163], v[104:107]
	v_mfma_f32_16x16x32_bf16 v[28:31], v[144:147], v[174:177], v[28:31]
	v_mfma_f32_16x16x32_bf16 v[20:23], v[152:155], v[174:177], v[20:23]
	v_mfma_f32_16x16x32_bf16 v[8:11], v[144:147], v[192:195], v[8:11]
	v_mfma_f32_16x16x32_bf16 v[12:15], v[152:155], v[192:195], v[12:15]
	v_mfma_f32_16x16x32_bf16 v[40:43], v[144:147], v[200:203], v[40:43]
	v_mfma_f32_16x16x32_bf16 v[44:47], v[152:155], v[200:203], v[44:47]
	v_mfma_f32_16x16x32_bf16 v[120:123], v[148:151], v[170:173], v[120:123]
	v_mfma_f32_16x16x32_bf16 v[104:107], v[156:159], v[170:173], v[104:107]
	v_mfma_f32_16x16x32_bf16 v[28:31], v[148:151], v[188:191], v[28:31]
	v_mfma_f32_16x16x32_bf16 v[20:23], v[156:159], v[188:191], v[20:23]
	v_mfma_f32_16x16x32_bf16 v[8:11], v[148:151], v[196:199], v[8:11]
	v_mfma_f32_16x16x32_bf16 v[12:15], v[156:159], v[196:199], v[12:15]
	v_mfma_f32_16x16x32_bf16 v[40:43], v[148:151], v[204:207], v[40:43]
	v_mfma_f32_16x16x32_bf16 v[44:47], v[156:159], v[204:207], v[44:47]
	s_setprio 0
	s_barrier
; __device__ __forceinline__ int lane_id() { int l; asm volatile("v_mbcnt_lo_u32_b32 %0, -1, 0\n\tv_mbcnt_hi_u32_b32 %0, -1, %0" : "=v"(l)); return l; }
; #define PG8_BAR __builtin_amdgcn_s_barrier()
; template <class Epi, class Sched, bool ALIGN_EPI = false, bool SP2 = true>
; __device__ __forceinline__ void gemm_phase(PG8_LAS unsigned char* lds, const Gemm g, const Sched& S, const Epi& E, int wid) {
;     ...
;         if constexpr (TWO) { const int l1_ = lane_id(); aoff = lds_byte(wr * 64 + (l1_ & 15), (l1_ >> 4) * 8); boff = lds_byte(wc * 32 + (l1_ & 15), (l1_ >> 4) * 8); }
;         if constexpr (ZC) { { const int t = 0; PG8_TRIP(F8A || F8S1, true); }
;             for (int t = 2; t < nt1; t += 2) PG8_TRIP(F8A || F8S1, false); }
;         else { for (int t = 0; t < nt1; t += 2) PG8_TRIP(F8A || F8S1, false); }
;         if constexpr (TWO) { E.mid(acc, cur, wr, wc, fr, fq);
;             { const int l2_ = lane_id(); aoff = lds_byte(wr * 64 + (l2_ & 15), (l2_ >> 4) * 8); boff = lds_byte(wc * 32 + (l2_ & 15), (l2_ >> 4) * 8); }
;             for (int t = nt1; t < nt; t += 2) PG8_TRIP(F8A, false); }
;         if constexpr (ALIGN_EPI) { if (wr == 0) PG8_BAR; }
	ds_read_b128 v[160:163], v182 offset:49152
	ds_read_b128 v[170:173], v182 offset:50176
	ds_read_b128 v[174:177], v182 offset:51200
	ds_read_b128 v[188:191], v182 offset:52224
	ds_read_b128 v[192:195], v182 offset:53248
	ds_read_b128 v[196:199], v182 offset:54272
	ds_read_b128 v[200:203], v182 offset:55296
	ds_read_b128 v[204:207], v182 offset:56320
	s_mov_b32 s42, m0
	s_mov_b32 m0, s69
	s_nop 0
	global_load_lds_dwordx4 v179, s[40:41]
	s_mov_b32 m0, s42
	s_mov_b32 s40, m0
	s_mov_b32 m0, s70
	s_nop 0
	global_load_lds_dwordx4 v179, s[38:39]
	s_mov_b32 m0, s40
	s_mov_b32 s38, m0
	s_mov_b32 m0, s73
	s_nop 0
	global_load_lds_dwordx4 v179, s[36:37]
	s_mov_b32 m0, s38
	s_mov_b32 s36, m0
	s_mov_b32 m0, s74
	s_nop 0
	global_load_lds_dwordx4 v179, s[26:27]
	s_mov_b32 m0, s36
	s_mov_b32 s26, m0
	s_mov_b32 m0, s71
	s_nop 0
	global_load_lds_dwordx4 v179, s[8:9]
	s_mov_b32 m0, s26
	s_mov_b32 s8, m0
	s_mov_b32 m0, s72
	s_nop 0
	global_load_lds_dwordx4 v179, s[24:25]
	s_mov_b32 m0, s8
	s_waitcnt vmcnt(8)
	s_waitcnt lgkmcnt(0)
	s_barrier
	s_setprio 1
	s_waitcnt lgkmcnt(7)
	v_mfma_f32_16x16x32_bf16 v[56:59], v[128:131], v[160:163], v[56:59]
	v_mfma_f32_16x16x32_bf16 v[48:51], v[136:139], v[160:163], v[48:51]
	s_waitcnt lgkmcnt(5)
	v_mfma_f32_16x16x32_bf16 v[64:67], v[128:131], v[174:177], v[64:67]
	v_mfma_f32_16x16x32_bf16 v[68:71], v[136:139], v[174:177], v[68:71]
	s_waitcnt lgkmcnt(3)
	v_mfma_f32_16x16x32_bf16 v[80:83], v[128:131], v[192:195], v[80:83]
	v_mfma_f32_16x16x32_bf16 v[84:87], v[136:139], v[192:195], v[84:87]
	s_waitcnt lgkmcnt(1)
	v_mfma_f32_16x16x32_bf16 v[100:103], v[128:131], v[200:203], v[100:103]
	v_mfma_f32_16x16x32_bf16 v[96:99], v[136:139], v[200:203], v[96:99]
	v_mfma_f32_16x16x32_bf16 v[56:59], v[132:135], v[170:173], v[56:59]
	v_mfma_f32_16x16x32_bf16 v[48:51], v[140:143], v[170:173], v[48:51]
	v_mfma_f32_16x16x32_bf16 v[64:67], v[132:135], v[188:191], v[64:67]
	v_mfma_f32_16x16x32_bf16 v[68:71], v[140:143], v[188:191], v[68:71]
	v_mfma_f32_16x16x32_bf16 v[80:83], v[132:135], v[196:199], v[80:83]
	v_mfma_f32_16x16x32_bf16 v[84:87], v[140:143], v[196:199], v[84:87]
	s_waitcnt lgkmcnt(0)
	v_mfma_f32_16x16x32_bf16 v[100:103], v[132:135], v[204:207], v[100:103]
	v_mfma_f32_16x16x32_bf16 v[96:99], v[140:143], v[204:207], v[96:99]
	s_setprio 0
	s_setprio 1
	v_mfma_f32_16x16x32_bf16 v[60:63], v[144:147], v[160:163], v[60:63]
	v_mfma_f32_16x16x32_bf16 v[52:55], v[152:155], v[160:163], v[52:55]
	v_mfma_f32_16x16x32_bf16 v[72:75], v[144:147], v[174:177], v[72:75]
	v_mfma_f32_16x16x32_bf16 v[76:79], v[152:155], v[174:177], v[76:79]
	v_mfma_f32_16x16x32_bf16 v[88:91], v[144:147], v[192:195], v[88:91]
	v_mfma_f32_16x16x32_bf16 v[92:95], v[152:155], v[192:195], v[92:95]
	v_mfma_f32_16x16x32_bf16 v[116:119], v[144:147], v[200:203], v[116:119]
	v_mfma_f32_16x16x32_bf16 v[112:115], v[152:155], v[200:203], v[112:115]
	v_mfma_f32_16x16x32_bf16 v[60:63], v[148:151], v[170:173], v[60:63]
	v_mfma_f32_16x16x32_bf16 v[52:55], v[156:159], v[170:173], v[52:55]
	v_mfma_f32_16x16x32_bf16 v[72:75], v[148:151], v[188:191], v[72:75]
	v_mfma_f32_16x16x32_bf16 v[76:79], v[156:159], v[188:191], v[76:79]
	v_mfma_f32_16x16x32_bf16 v[88:91], v[148:151], v[196:199], v[88:91]
	v_mfma_f32_16x16x32_bf16 v[92:95], v[156:159], v[196:199], v[92:95]
	v_mfma_f32_16x16x32_bf16 v[116:119], v[148:151], v[204:207], v[116:119]
	v_mfma_f32_16x16x32_bf16 v[112:115], v[156:159], v[204:207], v[112:115]
	s_setprio 0
	s_barrier
	s_mov_b32 s96, s23
	s_cbranch_scc0 .LBB0_932
	s_and_b64 vcc, exec, s[18:19]
	s_cbranch_vccz .LBB0_935
	s_barrier
